# prep row loop de-serialised: next row's four 1-KB loads prefetched, one counted vmcnt per row (was load/vmcnt(0)/store x4); plus GLA/attention load reorders and EpiRes hb store widening
# speedup vs baseline: 1.0032x; 1.0032x over previous
; DI int otid() { int t = threadIdx.x; asm volatile("" : "+v"(t)); return t; }
; DI void prep_phase(const Params& P, LAS unsigned char* lds) {
;   const int tid = otid(), wid = tid >> 6, lane = tid & 63;
;   const float* x = P.in[0];
;   bf16_t* hb = (bf16_t*)(P.ws + OFF_HB);
;   float* ss = (float*)(P.ws + OFF_SS);
;   for (int row = blockIdx.x * 8 + wid; row < T_TOK; row += gridDim.x * 8) {
;     const float* xr = x + (size_t)row * DM;
;     float q = 0.f;
; #pragma unroll
;     for (int e = 0; e < 4; ++e) {
;       const f32x4 v = *(const f32x4*)(xr + e * 256 + lane * 4);
.LBB0_621:
	v_mov_b32_e32 v10, v220
	v_readlane_b32 s0, v254, 16
	v_ashrrev_i32_e32 v0, 6, v10
	s_mov_b32 s61, 0x8000
	v_add_u32_e32 v2, s0, v0
	v_cmp_gt_i32_e32 vcc, s61, v2
	s_and_saveexec_b64 s[14:15], vcc
	v_readlane_b32 s52, v254, 8
	v_readlane_b32 s54, v254, 10
	s_mov_b32 s56, 0x24115d9a
	s_mov_b32 s62, 0x6dc9c883
	v_readlane_b32 s28, v253, 45
	v_readlane_b32 s53, v254, 9
	v_readlane_b32 s55, v254, 11
	v_readlane_b32 s29, v254, 17
	s_mov_b32 s57, 0x3fe7ff22
	s_mov_b32 s63, 0x3fc45f30
	s_mov_b32 s16, 0x7ffff
	s_mov_b32 s73, 0x9000
	s_cbranch_execz .LBB0_626
	s_waitcnt lgkmcnt(0)
	v_and_b32_e32 v3, 63, v10
	v_readlane_b32 s36, v253, 18
	v_lshlrev_b32_e32 v0, 2, v3
	v_lshlrev_b32_e32 v4, 4, v3
	v_mov_b32_e32 v5, v1
	v_readlane_b32 s37, v253, 19
	v_lshlrev_b32_e32 v6, 3, v3
	v_mov_b32_e32 v7, v1
	v_lshl_add_u64 v[4:5], s[36:37], 0, v[4:5]
	v_lshl_add_u64 v[6:7], s[58:59], 0, v[6:7]
	v_cmp_gt_u32_e32 vcc, 4, v3
	v_lshl_add_u64 v[8:9], s[6:7], 0, v[0:1]
	v_cmp_eq_u32_e64 s[0:1], 0, v3
	s_mov_b64 s[18:19], 0
	v_readlane_b32 s38, v253, 20
	v_readlane_b32 s39, v253, 21
	v_readlane_b32 s40, v253, 22
	v_readlane_b32 s41, v253, 23
	v_readlane_b32 s42, v253, 24
	v_readlane_b32 s43, v253, 25
	v_readlane_b32 s44, v253, 26
	v_readlane_b32 s45, v253, 27
	v_readlane_b32 s46, v253, 28
	v_readlane_b32 s47, v253, 29
	v_readlane_b32 s48, v253, 30
	v_readlane_b32 s49, v253, 31
	v_readlane_b32 s50, v253, 32
	v_readlane_b32 s51, v253, 33
	v_ashrrev_i32_e32 v3, 31, v2
	v_lshlrev_b64 v[30:31], 12, v[2:3]
	v_lshl_add_u64 v[30:31], v[4:5], 0, v[30:31]
	global_load_dwordx4 v[32:35], v[30:31], off
	global_load_dwordx4 v[36:39], v[30:31], off offset:1024
	global_load_dwordx4 v[40:43], v[30:31], off offset:2048
	global_load_dwordx4 v[44:47], v[30:31], off offset:3072
	s_waitcnt vmcnt(0)
	s_branch .Lprep_go

; DI unsigned cvt_pk(float lo, float hi) { unsigned r; asm("v_cvt_pk_bf16_f32 %0, %1, %2" : "=v"(r) : "v"(lo), "v"(hi)); return r; }
; DI void prep_phase(const Params& P, LAS unsigned char* lds) {
;     ...
;   for (int row = blockIdx.x * 8 + wid; row < T_TOK; row += gridDim.x * 8) {
;     const float* xr = x + (size_t)row * DM;
;     float q = 0.f;
; #pragma unroll
;     for (int e = 0; e < 4; ++e) {
;       const f32x4 v = *(const f32x4*)(xr + e * 256 + lane * 4);
;       q += v[0] * v[0] + v[1] * v[1] + v[2] * v[2] + v[3] * v[3];
;       u32x2 w; w.x = cvt_pk(v[0], v[1]); w.y = cvt_pk(v[2], v[3]);
;       *(u32x2*)(hb + (size_t)row * DM + e * 256 + lane * 4) = w;
;     }
; #pragma unroll
;     for (int o = 1; o < 64; o <<= 1) q += __shfl_xor(q, o);
;     if (lane < 4) ss[(size_t)row * 4 + lane] = (lane == 0) ? q : 0.f;
;   }
.LBB0_624:
	s_waitcnt vmcnt(4)
.Lprep_go:
	v_ashrrev_i32_e32 v3, 31, v2
	v_lshlrev_b64 v[16:17], 11, v[2:3]
	v_lshl_add_u64 v[28:29], v[6:7], 0, v[16:17]
	v_mov_b64_e32 v[12:13], v[32:33]
	v_mov_b64_e32 v[14:15], v[34:35]
	v_mov_b64_e32 v[16:17], v[36:37]
	v_mov_b64_e32 v[18:19], v[38:39]
	v_mov_b64_e32 v[20:21], v[40:41]
	v_mov_b64_e32 v[22:23], v[42:43]
	v_mov_b64_e32 v[24:25], v[44:45]
	v_mov_b64_e32 v[26:27], v[46:47]
	v_add_u32_e32 v30, s29, v2
	s_movk_i32 s13, 0x7fff
	v_cmp_ge_i32_e64 s[40:41], s13, v30
	s_and_saveexec_b64 s[36:37], s[40:41]
	v_ashrrev_i32_e32 v31, 31, v30
	v_lshlrev_b64 v[30:31], 12, v[30:31]
	v_lshl_add_u64 v[30:31], v[4:5], 0, v[30:31]
	global_load_dwordx4 v[32:35], v[30:31], off
	global_load_dwordx4 v[36:39], v[30:31], off offset:1024
	global_load_dwordx4 v[40:43], v[30:31], off offset:2048
	global_load_dwordx4 v[44:47], v[30:31], off offset:3072
	s_or_b64 exec, exec, s[36:37]
	v_cvt_pk_bf16_f32 v48, v12, v13
	v_cvt_pk_bf16_f32 v49, v14, v15
	global_store_dwordx2 v[28:29], v[48:49], off
	v_cvt_pk_bf16_f32 v50, v16, v17
	v_cvt_pk_bf16_f32 v51, v18, v19
	global_store_dwordx2 v[28:29], v[50:51], off offset:512
	v_cvt_pk_bf16_f32 v52, v20, v21
	v_cvt_pk_bf16_f32 v53, v22, v23
	global_store_dwordx2 v[28:29], v[52:53], off offset:1024
	v_cvt_pk_bf16_f32 v54, v24, v25
	v_cvt_pk_bf16_f32 v55, v26, v27
	global_store_dwordx2 v[28:29], v[54:55], off offset:1536
	v_and_b32_e32 v0, 64, v224
	s_waitcnt lgkmcnt(0)
	v_xor_b32_e32 v11, 1, v224
	v_add_u32_e32 v0, 64, v0
	v_cmp_lt_i32_e64 s[40:41], v11, v0
	v_mul_f32_e32 v13, v13, v13
	v_fmac_f32_e32 v13, v12, v12
	v_fmac_f32_e32 v13, v14, v14
	v_fmac_f32_e32 v13, v15, v15
	v_mul_f32_e32 v12, v17, v17
	v_fmac_f32_e32 v12, v16, v16
	v_fmac_f32_e32 v12, v18, v18
	v_fmac_f32_e32 v12, v19, v19
	v_add_f32_e32 v12, v13, v12
	v_mul_f32_e32 v13, v21, v21
	v_fmac_f32_e32 v13, v20, v20
	v_fmac_f32_e32 v13, v22, v22
	v_fmac_f32_e32 v13, v23, v23
	v_add_f32_e32 v12, v12, v13
	v_mul_f32_e32 v13, v25, v25
	v_fmac_f32_e32 v13, v24, v24
	v_fmac_f32_e32 v13, v26, v26
	v_cndmask_b32_e64 v11, v224, v11, s[40:41]
	v_fmac_f32_e32 v13, v27, v27
	v_lshlrev_b32_e32 v11, 2, v11
	v_add_f32_e32 v12, v12, v13
	ds_bpermute_b32 v11, v11, v12
	v_xor_b32_e32 v13, 2, v224
	v_cmp_lt_i32_e64 s[40:41], v13, v0
	s_waitcnt lgkmcnt(0)
	v_add_f32_e32 v11, v12, v11
	v_cndmask_b32_e64 v13, v224, v13, s[40:41]
	v_lshlrev_b32_e32 v13, 2, v13
	ds_bpermute_b32 v12, v13, v11
	v_xor_b32_e32 v13, 4, v224
	v_cmp_lt_i32_e64 s[40:41], v13, v0
	s_waitcnt lgkmcnt(0)
	v_add_f32_e32 v11, v11, v12
	v_cndmask_b32_e64 v13, v224, v13, s[40:41]
	v_lshlrev_b32_e32 v13, 2, v13
	ds_bpermute_b32 v12, v13, v11
	v_xor_b32_e32 v13, 8, v224
	v_cmp_lt_i32_e64 s[40:41], v13, v0
	s_waitcnt lgkmcnt(0)
	v_add_f32_e32 v11, v11, v12
	v_cndmask_b32_e64 v13, v224, v13, s[40:41]
	v_lshlrev_b32_e32 v13, 2, v13
	ds_bpermute_b32 v12, v13, v11
	v_xor_b32_e32 v13, 16, v224
	v_cmp_lt_i32_e64 s[40:41], v13, v0
	s_waitcnt lgkmcnt(0)
	v_add_f32_e32 v11, v11, v12
	v_cndmask_b32_e64 v13, v224, v13, s[40:41]
	v_lshlrev_b32_e32 v13, 2, v13
	ds_bpermute_b32 v12, v13, v11
	v_xor_b32_e32 v13, 32, v224
	v_cmp_lt_i32_e64 s[40:41], v13, v0
	s_waitcnt lgkmcnt(0)
	v_add_f32_e32 v0, v11, v12
	v_cndmask_b32_e64 v13, v224, v13, s[40:41]
	v_lshlrev_b32_e32 v11, 2, v13
	ds_bpermute_b32 v11, v11, v0
	s_and_saveexec_b64 s[36:37], vcc
	s_cbranch_execz .LBB0_623
	s_waitcnt lgkmcnt(0)
	v_add_f32_e32 v0, v0, v11
	v_lshl_add_u64 v[12:13], v[2:3], 4, v[8:9]
	v_cndmask_b32_e64 v0, 0, v0, s[0:1]
	global_store_dword v[12:13], v0, off
	s_branch .LBB0_623
